# speedup vs baseline: 1.0100x; 1.0019x over previous
; #define LAS __attribute__((address_space(3)))
; #define MFMA32(a_, b_, c_) __builtin_amdgcn_mfma_f32_32x32x16_bf16((a_), (b_), (c_), 0, 0, 0)
; __device__ __forceinline__ int crow(int reg, int h) { return (reg & 3) + 8 * (reg >> 2) + 4 * h; }
; __device__ __forceinline__ void attn_fast(KArgs ap, int l, LAS unsigned char* lds, const Ctx cx) {
;     ...
;             bf16x8 qf[4]; { const bf16_t* qp = z + (tok0 + i0 + r) * DIN + ZQ + head * 64 + 8 * hh;
; #pragma unroll
;                 for (int ks = 0; ks < 4; ++ks) qf[ks] = *(const bf16x8*)(qp + 16 * ks); }
;             f32x16 st[5];
; #pragma unroll
;             for (int kt = 0; kt < 5; ++kt) {
; #pragma unroll
;                 for (int i = 0; i < 16; ++i) st[kt][i] = 0.f;
; #pragma unroll
;                 for (int ks = 0; ks < 4; ++ks) { const bf16x8 kf = *(const LAS bf16x8*)(KL + (i0 + 32 * kt + r) * 144 + (16 * ks + 8 * hh) * 2); st[kt] = MFMA32(kf, qf[ks], st[kt]); }
;             }
;             float m = sink2;
; #pragma unroll
;             for (int kt = 0; kt < 5; ++kt)
; #pragma unroll
;                 for (int i = 0; i < 16; ++i) { const int kl = 32 * kt + crow(i, hh);
;                     const bool valid = (kl > r) && (kl <= 128 + r) && (nb > 0 || i0 + kl >= 128);
;                     const float x = valid ? st[kt][i] * (0.125f * LOG2E) : -__builtin_inff();
;                     st[kt][i] = x; m = fmaxf(m, x); }
.LBB0_135:
	global_load_dwordx4 v[0:3], v[108:109], off offset:-64
	global_load_dwordx4 v[124:127], v[108:109], off offset:-32
	global_load_dwordx4 v[128:131], v[108:109], off
	global_load_dwordx4 v[80:83], v[108:109], off offset:32
	ds_read_b128 v[4:7], v123
	ds_read_b128 v[8:11], v123 offset:32
	s_add_i32 s26, s31, 1
	s_cmp_gt_u32 s31, 2
	s_cselect_b64 vcc, -1, 0
	s_or_b64 vcc, s[28:29], vcc
	s_cmp_gt_u32 s31, 1
	v_add_u32_e32 v122, 0x1200, v123
	s_waitcnt vmcnt(3) lgkmcnt(1)
	v_mfma_f32_32x32x16_bf16 v[64:79], v[4:7], v[0:3], 0
	ds_read_b128 v[4:7], v123 offset:64
	ds_read_b128 v[132:135], v123 offset:18464
	s_waitcnt vmcnt(2) lgkmcnt(2)
	v_mfma_f32_32x32x16_bf16 v[64:79], v[8:11], v[124:127], v[64:79]
	s_waitcnt vmcnt(1) lgkmcnt(1)
	v_mfma_f32_32x32x16_bf16 v[64:79], v[4:7], v[128:131], v[64:79]
	ds_read_b128 v[4:7], v123 offset:96
	s_waitcnt vmcnt(0) lgkmcnt(0)
	v_mfma_f32_32x32x16_bf16 v[64:79], v[4:7], v[80:83], v[64:79]
	ds_read_b128 v[4:7], v123 offset:4608
	s_waitcnt lgkmcnt(0)
	v_mfma_f32_32x32x16_bf16 v[48:63], v[4:7], v[0:3], 0
	ds_read_b128 v[4:7], v123 offset:4640
	s_nop 7
	v_mul_f32_e32 v64, 0x3e38aa3b, v64
	v_mul_f32_e32 v65, 0x3e38aa3b, v65
	v_cndmask_b32_e64 v64, v197, v64, s[80:81]
	v_cndmask_b32_e64 v65, v197, v65, s[82:83]
	v_mul_f32_e32 v66, 0x3e38aa3b, v66
	v_mul_f32_e32 v67, 0x3e38aa3b, v67
	s_waitcnt lgkmcnt(0)
	v_mfma_f32_32x32x16_bf16 v[48:63], v[4:7], v[124:127], v[48:63]
	ds_read_b128 v[4:7], v123 offset:4672
	v_cndmask_b32_e64 v66, v197, v66, s[84:85]
	v_cndmask_b32_e64 v67, v197, v67, s[86:87]
	v_mul_f32_e32 v68, 0x3e38aa3b, v68
	v_mul_f32_e32 v69, 0x3e38aa3b, v69
	v_cndmask_b32_e64 v68, v197, v68, s[88:89]
	v_cndmask_b32_e64 v69, v197, v69, s[90:91]
	s_waitcnt lgkmcnt(0)
	v_mfma_f32_32x32x16_bf16 v[48:63], v[4:7], v[128:131], v[48:63]
	ds_read_b128 v[4:7], v123 offset:4704
	v_mul_f32_e32 v70, 0x3e38aa3b, v70
	v_mul_f32_e32 v71, 0x3e38aa3b, v71
	v_cndmask_b32_e64 v70, v197, v70, s[92:93]
	v_cndmask_b32_e64 v71, v197, v71, s[94:95]
	v_mul_f32_e32 v72, 0x3e38aa3b, v72
	v_mul_f32_e32 v73, 0x3e38aa3b, v73
	s_waitcnt lgkmcnt(0)
	v_mfma_f32_32x32x16_bf16 v[48:63], v[4:7], v[80:83], v[48:63]
	ds_read_b128 v[4:7], v123 offset:9216
	v_cndmask_b32_e64 v72, v197, v72, s[96:97]
	v_cndmask_b32_e64 v73, v197, v73, s[14:15]
	v_mul_f32_e32 v74, 0x3e38aa3b, v74
	v_mul_f32_e32 v75, 0x3e38aa3b, v75
	v_cndmask_b32_e64 v74, v197, v74, s[4:5]
	v_cndmask_b32_e64 v75, v197, v75, s[6:7]
	s_waitcnt lgkmcnt(0)
	v_mfma_f32_32x32x16_bf16 v[32:47], v[4:7], v[0:3], 0
	ds_read_b128 v[4:7], v123 offset:9248
	v_mul_f32_e32 v76, 0x3e38aa3b, v76
	v_mul_f32_e32 v77, 0x3e38aa3b, v77
	v_cndmask_b32_e64 v76, v197, v76, s[0:1]
	v_cndmask_b32_e64 v77, v197, v77, s[8:9]
	v_mul_f32_e32 v78, 0x3e38aa3b, v78
	v_mul_f32_e32 v79, 0x3e38aa3b, v79
	s_waitcnt lgkmcnt(0)
	v_mfma_f32_32x32x16_bf16 v[32:47], v[4:7], v[124:127], v[32:47]
	ds_read_b128 v[4:7], v123 offset:9280
	v_cndmask_b32_e64 v78, v197, v78, s[10:11]
	v_cndmask_b32_e64 v79, v197, v79, s[12:13]
	v_mul_f32_e32 v48, 0x3e38aa3b, v48
	v_mul_f32_e32 v49, 0x3e38aa3b, v49
	v_cndmask_b32_e32 v48, v197, v48, vcc
	v_cndmask_b32_e32 v49, v197, v49, vcc
	s_waitcnt lgkmcnt(0)
	v_mfma_f32_32x32x16_bf16 v[32:47], v[4:7], v[128:131], v[32:47]
	ds_read_b128 v[4:7], v123 offset:9312
	v_mul_f32_e32 v50, 0x3e38aa3b, v50
	v_mul_f32_e32 v51, 0x3e38aa3b, v51
	v_cndmask_b32_e32 v50, v197, v50, vcc
	v_cndmask_b32_e32 v51, v197, v51, vcc
	v_mul_f32_e32 v52, 0x3e38aa3b, v52
	v_mul_f32_e32 v53, 0x3e38aa3b, v53
	s_waitcnt lgkmcnt(0)
	v_mfma_f32_32x32x16_bf16 v[32:47], v[4:7], v[80:83], v[32:47]
	ds_read_b128 v[4:7], v123 offset:13824
	v_cndmask_b32_e32 v52, v197, v52, vcc
	v_cndmask_b32_e32 v53, v197, v53, vcc
	v_mul_f32_e32 v54, 0x3e38aa3b, v54
	v_mul_f32_e32 v55, 0x3e38aa3b, v55
	v_cndmask_b32_e32 v54, v197, v54, vcc
	v_cndmask_b32_e32 v55, v197, v55, vcc
	s_waitcnt lgkmcnt(0)
	v_mfma_f32_32x32x16_bf16 v[16:31], v[4:7], v[0:3], 0
	ds_read_b128 v[4:7], v123 offset:13856
	v_mul_f32_e32 v56, 0x3e38aa3b, v56
	v_mul_f32_e32 v57, 0x3e38aa3b, v57
	v_cndmask_b32_e32 v56, v197, v56, vcc
	v_cndmask_b32_e32 v57, v197, v57, vcc
	v_mul_f32_e32 v58, 0x3e38aa3b, v58
	v_mul_f32_e32 v59, 0x3e38aa3b, v59
	s_waitcnt lgkmcnt(0)
	v_mfma_f32_32x32x16_bf16 v[16:31], v[4:7], v[124:127], v[16:31]
	ds_read_b128 v[4:7], v123 offset:13888
	v_mul_f32_e32 v60, 0x3e38aa3b, v60
	v_mul_f32_e32 v61, 0x3e38aa3b, v61
	v_mul_f32_e32 v62, 0x3e38aa3b, v62
	v_mul_f32_e32 v63, 0x3e38aa3b, v63
	v_cndmask_b32_e32 v58, v197, v58, vcc
	v_cndmask_b32_e32 v59, v197, v59, vcc
	s_waitcnt lgkmcnt(0)
	v_mfma_f32_32x32x16_bf16 v[16:31], v[4:7], v[128:131], v[16:31]
	ds_read_b128 v[4:7], v123 offset:13920
	v_cndmask_b32_e32 v60, v197, v60, vcc
	v_cndmask_b32_e32 v61, v197, v61, vcc
	v_cndmask_b32_e32 v62, v197, v62, vcc
	v_cndmask_b32_e32 v63, v197, v63, vcc
	s_cselect_b64 vcc, -1, 0
	s_or_b64 vcc, s[28:29], vcc
	s_waitcnt lgkmcnt(0)
	v_mfma_f32_32x32x16_bf16 v[16:31], v[4:7], v[80:83], v[16:31]
	ds_read_b128 v[4:7], v123 offset:18432
	v_mul_f32_e32 v32, 0x3e38aa3b, v32
	s_or_b32 s27, s31, s40
	s_cmp_eq_u32 s27, 0
	s_mov_b32 s31, s26
	s_nop 6
	v_mul_f32_e32 v16, 0x3e38aa3b, v16
	s_waitcnt lgkmcnt(0)
	v_mfma_f32_32x32x16_bf16 v[0:15], v[4:7], v[0:3], 0
	v_mul_f32_e32 v17, 0x3e38aa3b, v17
	v_mul_f32_e32 v18, 0x3e38aa3b, v18
	v_mul_f32_e32 v19, 0x3e38aa3b, v19
	v_mul_f32_e32 v20, 0x3e38aa3b, v20
	v_mul_f32_e32 v21, 0x3e38aa3b, v21
	v_mul_f32_e32 v22, 0x3e38aa3b, v22
	v_mul_f32_e32 v23, 0x3e38aa3b, v23
	v_mfma_f32_32x32x16_bf16 v[0:15], v[132:135], v[124:127], v[0:15]
	ds_read_b128 v[124:127], v123 offset:18496
	v_mul_f32_e32 v24, 0x3e38aa3b, v24
	v_mul_f32_e32 v25, 0x3e38aa3b, v25
	v_mul_f32_e32 v26, 0x3e38aa3b, v26
	v_mul_f32_e32 v27, 0x3e38aa3b, v27
	v_mul_f32_e32 v28, 0x3e38aa3b, v28
	v_mul_f32_e32 v29, 0x3e38aa3b, v29
	s_waitcnt lgkmcnt(0)
; #define LAS __attribute__((address_space(3)))
; #define MFMA32(a_, b_, c_) __builtin_amdgcn_mfma_f32_32x32x16_bf16((a_), (b_), (c_), 0, 0, 0)
; __device__ __forceinline__ int crow(int reg, int h) { return (reg & 3) + 8 * (reg >> 2) + 4 * h; }
; __device__ __forceinline__ void attn_fast(KArgs ap, int l, LAS unsigned char* lds, const Ctx cx) {
;     ...
;                 for (int ks = 0; ks < 4; ++ks) { const bf16x8 kf = *(const LAS bf16x8*)(KL + (i0 + 32 * kt + r) * 144 + (16 * ks + 8 * hh) * 2); st[kt] = MFMA32(kf, qf[ks], st[kt]); }
;             }
;             float m = sink2;
; #pragma unroll
;             for (int kt = 0; kt < 5; ++kt)
; #pragma unroll
;                 for (int i = 0; i < 16; ++i) { const int kl = 32 * kt + crow(i, hh);
;                     const bool valid = (kl > r) && (kl <= 128 + r) && (nb > 0 || i0 + kl >= 128);
;                     const float x = valid ? st[kt][i] * (0.125f * LOG2E) : -__builtin_inff();
;                     st[kt][i] = x; m = fmaxf(m, x); }
;             m = fmaxf(m, __shfl_xor(m, 32));
	v_mfma_f32_32x32x16_bf16 v[0:15], v[124:127], v[128:131], v[0:15]
	ds_read_b128 v[124:127], v123 offset:18528
	v_mul_f32_e32 v30, 0x3e38aa3b, v30
	v_mul_f32_e32 v31, 0x3e38aa3b, v31
	s_waitcnt lgkmcnt(0)
	v_mfma_f32_32x32x16_bf16 v[0:15], v[124:127], v[80:83], v[0:15]
	v_max3_f32 v80, v121, v64, v65
	v_max3_f32 v80, v80, v66, v67
	v_max3_f32 v80, v80, v68, v69
	v_max3_f32 v80, v80, v70, v71
	v_max3_f32 v80, v80, v72, v73
	v_max3_f32 v80, v80, v74, v75
	v_max3_f32 v80, v80, v76, v77
	v_max3_f32 v80, v80, v78, v79
	v_max3_f32 v80, v80, v48, v49
	v_max3_f32 v80, v80, v50, v51
	v_max3_f32 v80, v80, v52, v53
	v_max3_f32 v80, v80, v54, v55
	v_max3_f32 v80, v80, v56, v57
	v_max3_f32 v80, v80, v58, v59
	v_max3_f32 v80, v80, v60, v61
	v_cndmask_b32_e32 v81, v197, v32, vcc
	v_mul_f32_e32 v32, 0x3e38aa3b, v33
	v_max3_f32 v80, v80, v62, v63
	v_cndmask_b32_e32 v82, v197, v32, vcc
	v_mul_f32_e32 v33, 0x3e38aa3b, v34
	v_max3_f32 v32, v80, v81, v82
	v_cndmask_b32_e32 v80, v197, v33, vcc
	v_mul_f32_e32 v33, 0x3e38aa3b, v35
	v_cndmask_b32_e32 v83, v197, v33, vcc
	v_mul_f32_e32 v33, 0x3e38aa3b, v36
	v_cndmask_b32_e32 v123, v197, v33, vcc
	v_mul_f32_e32 v33, 0x3e38aa3b, v37
	v_cndmask_b32_e32 v124, v197, v33, vcc
	v_mul_f32_e32 v33, 0x3e38aa3b, v38
	v_cndmask_b32_e32 v125, v197, v33, vcc
	v_mul_f32_e32 v33, 0x3e38aa3b, v39
	v_cndmask_b32_e32 v126, v197, v33, vcc
	v_mul_f32_e32 v33, 0x3e38aa3b, v40
	v_cndmask_b32_e32 v127, v197, v33, vcc
	v_mul_f32_e32 v33, 0x3e38aa3b, v41
	v_cndmask_b32_e32 v128, v197, v33, vcc
	v_mul_f32_e32 v33, 0x3e38aa3b, v42
	v_max3_f32 v32, v32, v80, v83
	v_cndmask_b32_e32 v129, v197, v33, vcc
	v_mul_f32_e32 v33, 0x3e38aa3b, v43
	v_max3_f32 v32, v32, v123, v124
	v_cndmask_b32_e32 v130, v197, v33, vcc
	v_mul_f32_e32 v33, 0x3e38aa3b, v44
	v_max3_f32 v32, v32, v125, v126
	v_cndmask_b32_e32 v131, v197, v33, vcc
	v_mul_f32_e32 v33, 0x3e38aa3b, v45
	v_max3_f32 v32, v32, v127, v128
	v_cndmask_b32_e32 v132, v197, v33, vcc
	v_mul_f32_e32 v33, 0x3e38aa3b, v46
	v_max3_f32 v32, v32, v129, v130
	v_cndmask_b32_e32 v133, v197, v33, vcc
	v_mul_f32_e32 v33, 0x3e38aa3b, v47
	v_max3_f32 v32, v32, v131, v132
	v_cndmask_b32_e32 v134, v197, v33, vcc
	s_cselect_b64 vcc, -1, 0
	v_max3_f32 v32, v32, v133, v134
	v_cndmask_b32_e32 v16, v16, v197, vcc
	v_cndmask_b32_e32 v17, v17, v197, vcc
	v_max3_f32 v32, v32, v16, v17
	v_cndmask_b32_e32 v18, v18, v197, vcc
	v_cndmask_b32_e32 v19, v19, v197, vcc
	v_max3_f32 v32, v32, v18, v19
	v_cndmask_b32_e32 v20, v20, v197, vcc
	v_cndmask_b32_e32 v21, v21, v197, vcc
	v_max3_f32 v32, v32, v20, v21
	v_cndmask_b32_e32 v22, v22, v197, vcc
	v_cndmask_b32_e32 v23, v23, v197, vcc
	v_max3_f32 v32, v32, v22, v23
	v_cndmask_b32_e32 v24, v24, v197, vcc
	v_cndmask_b32_e32 v25, v25, v197, vcc
	v_max3_f32 v32, v32, v24, v25
	v_cndmask_b32_e32 v26, v26, v197, vcc
	v_cndmask_b32_e32 v27, v27, v197, vcc
	v_max3_f32 v32, v32, v26, v27
	v_cndmask_b32_e32 v28, v28, v197, vcc
	v_cndmask_b32_e32 v29, v29, v197, vcc
	v_max3_f32 v32, v32, v28, v29
	v_cndmask_b32_e32 v30, v30, v197, vcc
	v_cndmask_b32_e32 v31, v31, v197, vcc
	v_mul_f32_e32 v0, 0x3e38aa3b, v0
	v_mul_f32_e32 v1, 0x3e38aa3b, v1
	v_max3_f32 v32, v32, v30, v31
	v_cndmask_b32_e64 v0, v0, v197, s[16:17]
	v_cndmask_b32_e64 v1, v1, v197, s[18:19]
	v_mul_f32_e32 v2, 0x3e38aa3b, v2
	v_mul_f32_e32 v3, 0x3e38aa3b, v3
	v_max3_f32 v32, v32, v0, v1
	v_cndmask_b32_e64 v2, v2, v197, s[20:21]
	v_cndmask_b32_e64 v3, v3, v197, s[38:39]
	v_mul_f32_e32 v4, 0x3e38aa3b, v4
	v_mul_f32_e32 v5, 0x3e38aa3b, v5
	v_max3_f32 v32, v32, v2, v3
	v_cndmask_b32_e64 v4, v4, v197, s[56:57]
	v_cndmask_b32_e64 v5, v5, v197, s[58:59]
	v_mul_f32_e32 v6, 0x3e38aa3b, v6
	v_mul_f32_e32 v7, 0x3e38aa3b, v7
	v_max3_f32 v32, v32, v4, v5
	v_cndmask_b32_e64 v6, v6, v197, s[60:61]
	v_cndmask_b32_e64 v7, v7, v197, s[62:63]
	v_mul_f32_e32 v8, 0x3e38aa3b, v8
	v_mul_f32_e32 v9, 0x3e38aa3b, v9
	v_max3_f32 v32, v32, v6, v7
	v_cndmask_b32_e64 v8, v8, v197, s[64:65]
	v_cndmask_b32_e64 v9, v9, v197, s[66:67]
	v_mul_f32_e32 v10, 0x3e38aa3b, v10
	v_mul_f32_e32 v11, 0x3e38aa3b, v11
	v_max3_f32 v32, v32, v8, v9
	v_cndmask_b32_e64 v10, v10, v197, s[68:69]
	v_cndmask_b32_e64 v11, v11, v197, s[70:71]
	v_mul_f32_e32 v12, 0x3e38aa3b, v12
	v_mul_f32_e32 v13, 0x3e38aa3b, v13
	v_max3_f32 v32, v32, v10, v11
	v_cndmask_b32_e64 v12, v12, v197, s[72:73]
	v_cndmask_b32_e64 v13, v13, v197, s[74:75]
	v_mul_f32_e32 v14, 0x3e38aa3b, v14
	v_mul_f32_e32 v15, 0x3e38aa3b, v15
	v_max3_f32 v32, v32, v12, v13
	v_cndmask_b32_e64 v14, v14, v197, s[76:77]
	v_cndmask_b32_e64 v15, v15, v197, s[78:79]
	v_max3_f32 v32, v32, v14, v15
	ds_bpermute_b32 v33, v89, v32
	s_waitcnt lgkmcnt(0)
; __device__ __forceinline__ void attn_fast(KArgs ap, int l, LAS unsigned char* lds, const Ctx cx) {
;     ...
;             m = fmaxf(m, __shfl_xor(m, 32));
;             float lsum = 0.f;
; #pragma unroll
;             for (int kt = 0; kt < 5; ++kt)
; #pragma unroll
;                 for (int i = 0; i < 16; ++i) { const float pv = __builtin_amdgcn_exp2f(st[kt][i] - m); st[kt][i] = pv; lsum += pv; }
;             lsum += __shfl_xor(lsum, 32); lsum += __builtin_amdgcn_exp2f(sink2 - m);
	v_max_f32_e32 v33, v33, v33
	v_max_f32_e32 v142, v32, v33
	v_sub_f32_e32 v32, v64, v142
	v_exp_f32_e32 v145, v32
	v_sub_f32_e32 v33, v65, v142
	v_exp_f32_e32 v146, v33
	v_sub_f32_e32 v33, v66, v142
	v_exp_f32_e32 v147, v33
	v_sub_f32_e32 v33, v67, v142
	v_exp_f32_e32 v148, v33
	v_sub_f32_e32 v33, v68, v142
	v_add_f32_e32 v32, 0, v145
	v_exp_f32_e32 v149, v33
	v_sub_f32_e32 v33, v69, v142
	v_add_f32_e32 v32, v146, v32
	v_exp_f32_e32 v150, v33
	v_sub_f32_e32 v33, v70, v142
	v_add_f32_e32 v32, v147, v32
	v_exp_f32_e32 v151, v33
	v_sub_f32_e32 v33, v71, v142
	v_add_f32_e32 v32, v148, v32
	v_exp_f32_e32 v152, v33
	v_add_f32_e32 v32, v149, v32
	v_add_f32_e32 v32, v150, v32
	v_add_f32_e32 v32, v151, v32
	v_add_f32_e32 v33, v152, v32
	v_sub_f32_e32 v32, v72, v142
	v_exp_f32_e32 v32, v32
	v_sub_f32_e32 v40, v79, v142
	v_exp_f32_e32 v40, v40
	v_sub_f32_e32 v64, v126, v142
	v_add_f32_e32 v34, v32, v33
	v_sub_f32_e32 v33, v73, v142
	v_exp_f32_e32 v33, v33
	v_exp_f32_e32 v64, v64
	v_sub_f32_e32 v72, v134, v142
	v_exp_f32_e32 v72, v72
	v_add_f32_e32 v35, v33, v34
	v_sub_f32_e32 v34, v74, v142
	v_exp_f32_e32 v34, v34
	v_sub_f32_e32 v16, v16, v142
	v_sub_f32_e32 v17, v17, v142
	v_sub_f32_e32 v0, v0, v142
	v_add_f32_e32 v36, v34, v35
	v_sub_f32_e32 v35, v75, v142
	v_exp_f32_e32 v35, v35
	v_exp_f32_e32 v126, v0
	v_sub_f32_e32 v1, v1, v142
	v_add_f32_e32 v37, v35, v36
	v_sub_f32_e32 v36, v76, v142
	v_exp_f32_e32 v36, v36
	s_nop 0
	v_add_f32_e32 v38, v36, v37
	v_sub_f32_e32 v37, v77, v142
	v_exp_f32_e32 v37, v37
	s_nop 0
	v_add_f32_e32 v39, v37, v38
	v_sub_f32_e32 v38, v78, v142
	v_exp_f32_e32 v38, v38
	s_nop 0
	v_add_f32_e32 v39, v38, v39
	v_add_f32_e32 v41, v40, v39
	v_sub_f32_e32 v39, v48, v142
	v_exp_f32_e32 v39, v39
	v_sub_f32_e32 v48, v55, v142
	v_exp_f32_e32 v48, v48
	v_add_f32_e32 v42, v39, v41
	v_sub_f32_e32 v41, v49, v142
	v_exp_f32_e32 v41, v41
	s_nop 0
	v_add_f32_e32 v43, v41, v42
	v_sub_f32_e32 v42, v50, v142
	v_exp_f32_e32 v42, v42
	s_nop 0
	v_add_f32_e32 v44, v42, v43
	v_sub_f32_e32 v43, v51, v142
	v_exp_f32_e32 v43, v43
	s_nop 0
	v_add_f32_e32 v45, v43, v44
	v_sub_f32_e32 v44, v52, v142
	v_exp_f32_e32 v44, v44
	s_nop 0
	v_add_f32_e32 v46, v44, v45
	v_sub_f32_e32 v45, v53, v142
	v_exp_f32_e32 v45, v45
	s_nop 0
	v_add_f32_e32 v47, v45, v46
	v_sub_f32_e32 v46, v54, v142
	v_exp_f32_e32 v46, v46
	s_nop 0
	v_add_f32_e32 v47, v46, v47
	v_add_f32_e32 v49, v48, v47
	v_sub_f32_e32 v47, v56, v142
	v_exp_f32_e32 v47, v47
	v_sub_f32_e32 v56, v63, v142
	v_exp_f32_e32 v56, v56
	v_add_f32_e32 v50, v47, v49
	v_sub_f32_e32 v49, v57, v142
	v_exp_f32_e32 v49, v49
	s_nop 0
	v_add_f32_e32 v51, v49, v50
	v_sub_f32_e32 v50, v58, v142
	v_exp_f32_e32 v50, v50
	s_nop 0
	v_add_f32_e32 v52, v50, v51
	v_sub_f32_e32 v51, v59, v142
	v_exp_f32_e32 v51, v51
	s_nop 0
	v_add_f32_e32 v53, v51, v52
	v_sub_f32_e32 v52, v60, v142
	v_exp_f32_e32 v52, v52
	s_nop 0
	v_add_f32_e32 v54, v52, v53
	v_sub_f32_e32 v53, v61, v142
	v_exp_f32_e32 v53, v53
	s_nop 0
	v_add_f32_e32 v55, v53, v54
	v_sub_f32_e32 v54, v62, v142
	v_exp_f32_e32 v54, v54
	s_nop 0
	v_add_f32_e32 v55, v54, v55
	v_add_f32_e32 v57, v56, v55
	v_sub_f32_e32 v55, v81, v142
	v_exp_f32_e32 v55, v55
	s_nop 0
	v_add_f32_e32 v58, v55, v57
	v_sub_f32_e32 v57, v82, v142
	v_exp_f32_e32 v57, v57
	s_nop 0
	v_add_f32_e32 v59, v57, v58
	v_sub_f32_e32 v58, v80, v142
	v_exp_f32_e32 v58, v58
	s_nop 0
	v_add_f32_e32 v60, v58, v59
	v_sub_f32_e32 v59, v83, v142
	v_exp_f32_e32 v59, v59
	s_nop 0
	v_add_f32_e32 v61, v59, v60
	v_sub_f32_e32 v60, v123, v142
	v_exp_f32_e32 v60, v60
	s_nop 0
	v_add_f32_e32 v62, v60, v61
	v_sub_f32_e32 v61, v124, v142
	v_exp_f32_e32 v61, v61
	s_nop 0
	v_add_f32_e32 v63, v61, v62
	v_sub_f32_e32 v62, v125, v142
	v_exp_f32_e32 v62, v62
	s_nop 0
	v_add_f32_e32 v63, v62, v63
	v_add_f32_e32 v65, v64, v63
	v_sub_f32_e32 v63, v127, v142
	v_exp_f32_e32 v63, v63
	s_nop 0
	v_add_f32_e32 v66, v63, v65
	v_sub_f32_e32 v65, v128, v142
	v_exp_f32_e32 v65, v65
	v_exp_f32_e32 v128, v1
	v_sub_f32_e32 v1, v2, v142
	v_sub_f32_e32 v2, v121, v142
	v_add_f32_e32 v67, v65, v66
	v_sub_f32_e32 v66, v129, v142
	v_exp_f32_e32 v66, v66
	v_exp_f32_e32 v129, v1
	v_sub_f32_e32 v1, v3, v142
	v_add_f32_e32 v68, v66, v67
	v_sub_f32_e32 v67, v130, v142
	v_exp_f32_e32 v67, v67
	v_exp_f32_e32 v130, v1
	v_sub_f32_e32 v1, v4, v142
	v_add_f32_e32 v69, v67, v68
	v_sub_f32_e32 v68, v131, v142
	v_exp_f32_e32 v68, v68
	v_exp_f32_e32 v131, v1
	v_sub_f32_e32 v1, v5, v142
	v_add_f32_e32 v70, v68, v69
	v_sub_f32_e32 v69, v132, v142
	v_exp_f32_e32 v69, v69
	v_exp_f32_e32 v132, v1
	v_sub_f32_e32 v1, v6, v142
	v_add_f32_e32 v71, v69, v70
	v_sub_f32_e32 v70, v133, v142
	v_exp_f32_e32 v70, v70
	v_exp_f32_e32 v133, v1
	v_sub_f32_e32 v1, v7, v142
	v_exp_f32_e32 v135, v1
	v_add_f32_e32 v71, v70, v71
	v_add_f32_e32 v73, v72, v71
	v_exp_f32_e32 v71, v16
	v_sub_f32_e32 v1, v8, v142
	v_exp_f32_e32 v134, v1
	v_sub_f32_e32 v1, v9, v142
	v_add_f32_e32 v16, v71, v73
	v_exp_f32_e32 v73, v17
	v_sub_f32_e32 v17, v18, v142
	v_exp_f32_e32 v74, v17
	v_sub_f32_e32 v17, v19, v142
	v_exp_f32_e32 v75, v17
	v_sub_f32_e32 v17, v20, v142
	v_exp_f32_e32 v76, v17
	v_sub_f32_e32 v17, v21, v142
	v_add_f32_e32 v16, v73, v16
	v_exp_f32_e32 v77, v17
	v_sub_f32_e32 v17, v22, v142
	v_add_f32_e32 v16, v74, v16
	v_exp_f32_e32 v78, v17
	v_sub_f32_e32 v17, v23, v142
	v_add_f32_e32 v16, v75, v16
	v_exp_f32_e32 v80, v17
	v_sub_f32_e32 v17, v24, v142
	v_add_f32_e32 v16, v76, v16
	v_exp_f32_e32 v79, v17
	v_sub_f32_e32 v17, v25, v142
	v_add_f32_e32 v16, v77, v16
	v_exp_f32_e32 v81, v17
	v_sub_f32_e32 v17, v26, v142
	v_add_f32_e32 v16, v78, v16
	v_exp_f32_e32 v82, v17
	v_sub_f32_e32 v17, v27, v142
	v_add_f32_e32 v16, v80, v16
	v_exp_f32_e32 v83, v17
	v_sub_f32_e32 v17, v28, v142
	v_add_f32_e32 v16, v79, v16
	v_exp_f32_e32 v123, v17
	v_sub_f32_e32 v17, v29, v142
	v_add_f32_e32 v16, v81, v16
	v_exp_f32_e32 v124, v17
	v_sub_f32_e32 v17, v30, v142
	v_add_f32_e32 v16, v82, v16
	v_exp_f32_e32 v125, v17
	v_sub_f32_e32 v17, v31, v142
	v_add_f32_e32 v16, v83, v16
	v_exp_f32_e32 v127, v17
	v_add_f32_e32 v16, v123, v16
	v_add_f32_e32 v16, v124, v16
	v_add_f32_e32 v16, v125, v16
	v_add_f32_e32 v16, v127, v16
	v_add_f32_e32 v0, v126, v16
	v_add_f32_e32 v0, v128, v0
	v_add_f32_e32 v0, v129, v0
	v_add_f32_e32 v0, v130, v0
	v_add_f32_e32 v0, v131, v0
	v_add_f32_e32 v0, v132, v0
	v_exp_f32_e32 v136, v1
	v_sub_f32_e32 v1, v10, v142
	v_add_f32_e32 v0, v133, v0
	v_exp_f32_e32 v137, v1
	v_sub_f32_e32 v1, v11, v142
	v_add_f32_e32 v0, v135, v0
	v_exp_f32_e32 v138, v1
	v_sub_f32_e32 v1, v12, v142
	v_add_f32_e32 v0, v134, v0
	v_exp_f32_e32 v139, v1
	v_sub_f32_e32 v1, v13, v142
	v_add_f32_e32 v0, v136, v0
	v_exp_f32_e32 v140, v1
	v_sub_f32_e32 v1, v14, v142
	v_add_f32_e32 v0, v137, v0
	v_exp_f32_e32 v141, v1
	v_sub_f32_e32 v1, v15, v142
	v_add_f32_e32 v0, v138, v0
	v_exp_f32_e32 v143, v1
	v_add_f32_e32 v0, v139, v0
	v_add_f32_e32 v0, v140, v0
	v_add_f32_e32 v0, v141, v0
	v_add_f32_e32 v0, v143, v0
	ds_bpermute_b32 v1, v89, v0
	v_exp_f32_e32 v142, v2
	s_waitcnt lgkmcnt(0)
; #define LAS __attribute__((address_space(3)))
; __device__ __forceinline__ unsigned pk2(float lo, float hi) { return f2bf(lo) | (f2bf(hi) << 16); }
; #define MFMA32(a_, b_, c_) __builtin_amdgcn_mfma_f32_32x32x16_bf16((a_), (b_), (c_), 0, 0, 0)
; __device__ __forceinline__ void attn_fast(KArgs ap, int l, LAS unsigned char* lds, const Ctx cx) {
;     ...
;             f32x16 o[2];
; #pragma unroll
;             for (int i = 0; i < 16; ++i) { o[0][i] = 0.f; o[1][i] = 0.f; }
; #pragma unroll
;             for (int kt = 0; kt < 5; ++kt)
; #pragma unroll
;                 for (int s2 = 0; s2 < 2; ++s2) {
;                     const bf16x8 pf = pack8(st[kt][8 * s2], st[kt][8 * s2 + 1], st[kt][8 * s2 + 2], st[kt][8 * s2 + 3], st[kt][8 * s2 + 4], st[kt][8 * s2 + 5], st[kt][8 * s2 + 6], st[kt][8 * s2 + 7]);
; #pragma unroll
;                     for (int dt = 0; dt < 2; ++dt) { const LAS unsigned char* va = VTL + (dt * 32 + r) * 520 + (i0 + 32 * kt + 16 * s2 + 4 * hh) * 2;
;                         const u32x2 lo = *(const LAS u32x2*)va, hi = *(const LAS u32x2*)(va + 16);
;                         const u32x4 vv = (u32x4){lo.x, lo.y, hi.x, hi.y};
;                         o[dt] = MFMA32(__builtin_bit_cast(bf16x8, vv), pf, o[dt]); }
;                 }
;             const float inv = 1.0f / lsum;
;             bf16_t* yp = y + (tok0 + i0 + r) * DM + YA + head * 64 + 4 * hh;
; #pragma unroll
;             for (int dt = 0; dt < 2; ++dt)
; #pragma unroll
;                 for (int q4 = 0; q4 < 4; ++q4) { u32x2 w; w.x = pk2(o[dt][4 * q4] * inv, o[dt][4 * q4 + 1] * inv); w.y = pk2(o[dt][4 * q4 + 2] * inv, o[dt][4 * q4 + 3] * inv);
;                     *(u32x2*)(yp + dt * 32 + 8 * q4) = w; }
	v_add_f32_e32 v144, v0, v1
	s_nop 1
	v_cvt_pk_bf16_f32 v0, v145, v146
	v_cvt_pk_bf16_f32 v1, v147, v148
	v_cvt_pk_bf16_f32 v2, v149, v150
	v_cvt_pk_bf16_f32 v3, v151, v152
	s_nop 1
	v_add_u32_e32 v145, s30, v114
	ds_read2_b64 v[4:7], v145 offset0:32 offset1:34
	v_add_u32_e32 v150, s30, v113
	s_waitcnt lgkmcnt(0)
	v_mfma_f32_32x32x16_bf16 v[16:31], v[4:7], v[0:3], 0
	ds_read2_b64 v[4:7], v150 offset0:32 offset1:34
	s_nop 1
	v_cvt_pk_bf16_f32 v146, v32, v33
	v_cvt_pk_bf16_f32 v147, v34, v35
	v_cvt_pk_bf16_f32 v148, v36, v37
	v_cvt_pk_bf16_f32 v149, v38, v40
	s_nop 1
	ds_read2_b64 v[32:35], v145 offset0:36 offset1:38
	s_add_i32 s30, s30, 64
	s_cmp_eq_u32 s30, 0
	s_waitcnt lgkmcnt(0)
	v_mfma_f32_32x32x16_bf16 v[16:31], v[32:35], v[146:149], v[16:31]
	ds_read2_b64 v[32:35], v150 offset0:36 offset1:38
	v_mfma_f32_32x32x16_bf16 v[0:15], v[4:7], v[0:3], 0
	s_waitcnt lgkmcnt(0)
	v_mfma_f32_32x32x16_bf16 v[0:15], v[32:35], v[146:149], v[0:15]
	ds_read2_b64 v[200:203], v145 offset0:40 offset1:42
	ds_read2_b64 v[186:189], v150 offset0:40 offset1:42
	s_nop 1
	v_cvt_pk_bf16_f32 v32, v39, v41
	v_cvt_pk_bf16_f32 v33, v42, v43
	v_cvt_pk_bf16_f32 v34, v44, v45
	v_cvt_pk_bf16_f32 v35, v46, v48
	s_nop 1
	s_waitcnt lgkmcnt(1)
	v_mfma_f32_32x32x16_bf16 v[16:31], v[200:203], v[32:35], v[16:31]
	s_waitcnt lgkmcnt(0)
	v_mfma_f32_32x32x16_bf16 v[0:15], v[186:189], v[32:35], v[0:15]
	ds_read2_b64 v[200:203], v145 offset0:44 offset1:46
	ds_read2_b64 v[186:189], v150 offset0:44 offset1:46
	s_nop 1
	v_cvt_pk_bf16_f32 v32, v47, v49
	v_cvt_pk_bf16_f32 v33, v50, v51
	v_cvt_pk_bf16_f32 v34, v52, v53
	v_cvt_pk_bf16_f32 v35, v54, v56
	s_nop 1
	s_waitcnt lgkmcnt(1)
	v_mfma_f32_32x32x16_bf16 v[16:31], v[200:203], v[32:35], v[16:31]
	s_waitcnt lgkmcnt(0)
	v_mfma_f32_32x32x16_bf16 v[0:15], v[186:189], v[32:35], v[0:15]
	ds_read2_b64 v[200:203], v145 offset0:48 offset1:50
	ds_read2_b64 v[186:189], v150 offset0:48 offset1:50
	s_nop 1
	v_cvt_pk_bf16_f32 v32, v55, v57
	v_cvt_pk_bf16_f32 v33, v58, v59
	v_cvt_pk_bf16_f32 v34, v60, v61
	v_cvt_pk_bf16_f32 v35, v62, v64
	s_nop 1
	s_waitcnt lgkmcnt(1)
	v_mfma_f32_32x32x16_bf16 v[16:31], v[200:203], v[32:35], v[16:31]
	s_waitcnt lgkmcnt(0)
	v_mfma_f32_32x32x16_bf16 v[0:15], v[186:189], v[32:35], v[0:15]
	ds_read2_b64 v[200:203], v145 offset0:52 offset1:54
	ds_read2_b64 v[186:189], v150 offset0:52 offset1:54
	s_nop 1
	v_cvt_pk_bf16_f32 v32, v63, v65
	v_cvt_pk_bf16_f32 v33, v66, v67
	v_cvt_pk_bf16_f32 v34, v68, v69
	v_cvt_pk_bf16_f32 v35, v70, v72
	s_nop 1
	s_waitcnt lgkmcnt(1)
	v_mfma_f32_32x32x16_bf16 v[16:31], v[200:203], v[32:35], v[16:31]
	s_waitcnt lgkmcnt(0)
	v_mfma_f32_32x32x16_bf16 v[0:15], v[186:189], v[32:35], v[0:15]
	ds_read2_b64 v[200:203], v145 offset0:56 offset1:58
	ds_read2_b64 v[186:189], v150 offset0:56 offset1:58
	s_nop 1
	v_cvt_pk_bf16_f32 v32, v71, v73
	v_cvt_pk_bf16_f32 v33, v74, v75
	v_cvt_pk_bf16_f32 v34, v76, v77
	v_cvt_pk_bf16_f32 v35, v78, v80
	s_nop 1
	s_waitcnt lgkmcnt(1)
	v_mfma_f32_32x32x16_bf16 v[16:31], v[200:203], v[32:35], v[16:31]
	s_waitcnt lgkmcnt(0)
	v_mfma_f32_32x32x16_bf16 v[0:15], v[186:189], v[32:35], v[0:15]
	s_nop 1
	v_cvt_pk_bf16_f32 v32, v79, v81
	v_cvt_pk_bf16_f32 v33, v82, v83
	v_cvt_pk_bf16_f32 v34, v123, v124
	v_cvt_pk_bf16_f32 v35, v125, v127
	s_nop 1
	ds_read2_b64 v[36:39], v145 offset0:60 offset1:62
	v_mov_b32_e32 v123, v122
	s_waitcnt lgkmcnt(0)
	v_mfma_f32_32x32x16_bf16 v[16:31], v[36:39], v[32:35], v[16:31]
	ds_read2_b64 v[36:39], v150 offset0:60 offset1:62
	s_waitcnt lgkmcnt(0)
	v_mfma_f32_32x32x16_bf16 v[0:15], v[36:39], v[32:35], v[0:15]
	ds_read2_b64 v[200:203], v145 offset0:64 offset1:66
	ds_read2_b64 v[186:189], v150 offset0:64 offset1:66
	s_nop 1
	v_cvt_pk_bf16_f32 v32, v126, v128
	v_cvt_pk_bf16_f32 v33, v129, v130
	v_cvt_pk_bf16_f32 v34, v131, v132
	v_cvt_pk_bf16_f32 v35, v133, v135
	s_nop 1
	s_waitcnt lgkmcnt(1)
	v_mfma_f32_32x32x16_bf16 v[16:31], v[200:203], v[32:35], v[16:31]
	s_waitcnt lgkmcnt(0)
	v_mfma_f32_32x32x16_bf16 v[0:15], v[186:189], v[32:35], v[0:15]
	ds_read2_b64 v[200:203], v145 offset0:68 offset1:70
	ds_read2_b64 v[186:189], v150 offset0:68 offset1:70
	s_nop 1
	v_cvt_pk_bf16_f32 v32, v134, v136
	v_cvt_pk_bf16_f32 v33, v137, v138
	v_cvt_pk_bf16_f32 v34, v139, v140
	v_cvt_pk_bf16_f32 v35, v141, v143
	s_nop 1
	s_waitcnt lgkmcnt(1)
	v_mfma_f32_32x32x16_bf16 v[16:31], v[200:203], v[32:35], v[16:31]
	s_waitcnt lgkmcnt(0)
	v_mfma_f32_32x32x16_bf16 v[0:15], v[186:189], v[32:35], v[0:15]
	v_add_f32_e32 v32, v142, v144
	v_div_scale_f32 v33, vcc, v32, v32, 1.0
	v_rcp_f32_e32 v34, v33
	s_nop 0
	v_fma_f32 v35, -v33, v34, 1.0
	v_fmac_f32_e32 v34, v35, v34
	v_div_scale_f32 v35, vcc, 1.0, v32, 1.0
	v_mul_f32_e32 v36, v35, v34
	v_fma_f32 v37, -v33, v36, v35
	v_fmac_f32_e32 v36, v37, v34
	v_fma_f32 v33, -v33, v36, v35
	v_div_fmas_f32 v33, v33, v34, v36
	v_div_fixup_f32 v32, v33, v32, 1.0
	v_mul_f32_e32 v16, v16, v32
	v_mul_f32_e32 v17, v17, v32
	v_mul_f32_e32 v18, v18, v32
	v_mul_f32_e32 v19, v19, v32
	v_mul_f32_e32 v20, v20, v32
	v_mul_f32_e32 v21, v21, v32
	v_mul_f32_e32 v22, v22, v32
	v_mul_f32_e32 v23, v23, v32
	v_mul_f32_e32 v24, v24, v32
	v_mul_f32_e32 v25, v25, v32
	v_mul_f32_e32 v26, v26, v32
	v_mul_f32_e32 v27, v27, v32
	v_mul_f32_e32 v28, v28, v32
	v_mul_f32_e32 v29, v29, v32
	v_mul_f32_e32 v30, v30, v32
	v_mul_f32_e32 v31, v31, v32
	v_mul_f32_e32 v0, v0, v32
	v_mul_f32_e32 v1, v1, v32
	v_mul_f32_e32 v2, v2, v32
	v_mul_f32_e32 v3, v3, v32
	v_mul_f32_e32 v4, v4, v32
	v_mul_f32_e32 v5, v5, v32
	v_mul_f32_e32 v6, v6, v32
	v_mul_f32_e32 v7, v7, v32
	v_mul_f32_e32 v8, v8, v32
	v_mul_f32_e32 v9, v9, v32
	v_mul_f32_e32 v10, v10, v32
	v_mul_f32_e32 v11, v11, v32
	v_mul_f32_e32 v12, v12, v32
	v_mul_f32_e32 v13, v13, v32
	v_mul_f32_e32 v14, v14, v32
	v_mul_f32_e32 v15, v15, v32
	v_cvt_pk_bf16_f32 v170, v16, v17
	v_cvt_pk_bf16_f32 v171, v18, v19
	v_cvt_pk_bf16_f32 v172, v20, v21
	v_cvt_pk_bf16_f32 v173, v22, v23
	v_cvt_pk_bf16_f32 v174, v24, v25
	v_cvt_pk_bf16_f32 v175, v26, v27
	v_cvt_pk_bf16_f32 v176, v28, v29
	v_cvt_pk_bf16_f32 v177, v30, v31
	v_cvt_pk_bf16_f32 v178, v0, v1
	v_cvt_pk_bf16_f32 v179, v2, v3
	v_cvt_pk_bf16_f32 v180, v4, v5
	v_cvt_pk_bf16_f32 v181, v6, v7
	v_cvt_pk_bf16_f32 v182, v8, v9
	v_cvt_pk_bf16_f32 v183, v10, v11
	v_cvt_pk_bf16_f32 v184, v12, v13
	v_cvt_pk_bf16_f32 v185, v14, v15
	global_store_dwordx2 v[110:111], v[170:171], off offset:-64
	global_store_dwordx2 v[110:111], v[172:173], off offset:-48
	global_store_dwordx2 v[110:111], v[174:175], off offset:-32
	global_store_dwordx2 v[110:111], v[176:177], off offset:-16
	global_store_dwordx2 v[110:111], v[178:179], off
	global_store_dwordx2 v[110:111], v[180:181], off offset:16
	global_store_dwordx2 v[110:111], v[182:183], off offset:32
	global_store_dwordx2 v[110:111], v[184:185], off offset:48
	s_mov_b64 vcc, 0x2c000
	v_lshl_add_u64 v[108:109], v[108:109], 0, vcc
	s_mov_b64 vcc, 0x20000
	v_lshl_add_u64 v[110:111], v[110:111], 0, vcc
	s_cbranch_scc0 .LBB0_135
; __device__ __forceinline__ void attn_fast(KArgs ap, int l, LAS unsigned char* lds, const Ctx cx) {
;     ...
;     for (int u = cx.bid; u < BATCH * (SEQ / 128) * 2; u += cx.nb) {
	v_readlane_b32 s0, v242, 9
	v_readlane_b32 s1, v242, 10
	s_add_i32 s41, s41, s55
	s_xor_b64 s[24:25], s[24:25], s[0:1]
	s_cmpk_gt_i32 s41, 0x1ff
	s_mov_b32 s80, s22
	s_cbranch_scc0 .LBB0_124
	v_readlane_b32 s78, v243, 14
	v_readlane_b32 s79, v243, 15
	s_mov_b32 s77, s23
	v_readlane_b32 s62, v243, 25
	v_readlane_b32 s57, v242, 8
	v_readlane_b32 s63, v243, 26
